# EpiUp conv-weight loads software-pipelined into free VGPRs + P0 weight transposes moved from fold WGs to modulation WGs (on top of sc1 stores)
# speedup vs baseline: 1.0200x; 1.0109x over previous
; #define LAS __attribute__((address_space(3)))
; __device__ __forceinline__ void p0_prologue(const Params& p, LAS unsigned char* lds) {
;     ...
;     LAS float* scr = (LAS float*)(lds + wave * 16384);
;     const int gw = blockIdx.x * NWAVES + wave, NGW = G * NWAVES;
;     constexpr int I_QK = 16 * 32, I_V = 16 * 16;
;     for (int it = gw; it < I_QK + I_V; it += NGW) {
;         int r = it;
;         if (r < I_QK) { const int kb = r >> 5, nb = r & 31; p0_transpose_item(p.w_in, 2048, 512 + nb * 32, DM, (bf16_t*)(p.ws + WS_WQK), nb * 32, nullptr, scr, kb, lane); continue; } r -= I_QK;
;         { const int kb = r >> 4, nb = r & 15; p0_transpose_item(p.w_in, 2048, 1536 + nb * 32, DM, (bf16_t*)(p.ws + WS_WA), 1024 + nb * 32, nullptr, scr, kb, lane); }
;     }
.LBB0_76:
	s_xor_b32 s98, s2, 0x80
	s_cmpk_eq_i32 s3, 0x100
	s_cselect_b32 s98, s98, s2
	v_lshl_add_u32 v14, s98, 3, v171
	s_movk_i32 s4, 0x300
	v_cmp_gt_i32_e32 vcc, s4, v14
	s_and_saveexec_b64 s[4:5], vcc
	s_cbranch_execz .LBB0_83
	v_lshlrev_b32_e32 v1, 3, v170
	v_lshrrev_b32_e32 v15, 3, v37
	v_and_b32_e32 v1, 56, v1
	v_lshl_add_u32 v0, v171, 14, 0
	v_mul_u32_u24_e32 v2, 0x84, v1
	v_lshlrev_b32_e32 v3, 2, v15
	v_lshl_add_u32 v8, v107, 2, v0
	v_add3_u32 v16, v0, v2, v3
	v_lshlrev_b32_e32 v0, 1, v1
	v_mov_b32_e32 v1, 0
	v_lshl_add_u64 v[2:3], s[8:9], 0, v[0:1]
	v_lshl_add_u64 v[4:5], s[34:35], 0, v[0:1]
	v_lshlrev_b32_e32 v0, 2, v171
	v_mul_u32_u24_e32 v9, 0x84, v106
	v_lshl_add_u32 v20, s98, 5, v0
	v_lshlrev_b32_e32 v0, 1, v171
	s_mov_b64 s[8:9], 0x300000
	v_mov_b32_e32 v37, v1
	v_lshl_add_u32 v21, s98, 4, v0
	v_lshlrev_b32_e32 v0, 5, v171
	v_add_u32_e32 v23, v8, v9
	s_lshl_b32 s10, s3, 3
	v_or_b32_e32 v17, 8, v15
	v_or_b32_e32 v18, 16, v15
	v_or_b32_e32 v19, 24, v15
	v_lshl_add_u64 v[4:5], v[4:5], 0, s[8:9]
	s_waitcnt lgkmcnt(0)
	v_lshl_add_u64 v[6:7], s[46:47], 0, v[36:37]
	s_lshl_b32 s11, s3, 5
	s_lshl_b32 s16, s3, 4
	v_lshl_add_u32 v22, s98, 8, v0
	s_lshl_b32 s17, s3, 8
	s_mov_b64 s[8:9], 0
	s_movk_i32 s18, 0x1ff
	s_mov_b64 s[12:13], 0x1800
	s_movk_i32 s19, 0x2ff
	v_add_u32_e32 v24, 0x400, v23
	v_add_u32_e32 v25, 0x800, v23
	v_add_u32_e32 v26, 0xc00, v23
	v_add_u32_e32 v27, 0x1000, v23
	v_add_u32_e32 v28, 0x1400, v23
	v_add_u32_e32 v29, 0x1800, v23
	v_add_u32_e32 v30, 0x1c00, v23
	s_branch .LBB0_79

; template <class Epi, class Sched>
; __device__ __forceinline__ void gemm_phase(LAS unsigned char* lds, const int K, const Sched& S, const Epi& E) {
;     ...
;         for (int a = 0; a < 2; ++a)
; #pragma unroll
;             for (int b = 0; b < 2; ++b)
; #pragma unroll
;                 for (int m = 0; m < 4; ++m)
; #pragma unroll
;                     for (int n = 0; n < 2; ++n) acc[a][b][m][n] = (f32x4){0.f, 0.f, 0.f, 0.f};
;     __device__ __forceinline__ void operator()(f32x4 (&acc)[2][2][4][2], const Unit& u, int wr, int wc, int fr, int fq) const {
;     ...
;                 const int col = bj * DFF + J0 + n * 4;
;                 const float csc = bj ? 0.6931471805599453f : 1.4426950408889634f;
;                 const f32x4 k0 = *(const f32x4*)(cw + col) * csc, k1 = *(const f32x4*)(cw + 2 * DFF + col) * csc, k2 = *(const f32x4*)(cw + 4 * DFF + col) * csc, kb = *(const f32x4*)(cb + col) * csc;
.LBB0_799:
	v_lshl_or_b32 v253, s10, 7, v157
	v_lshlrev_b32_e32 v253, 2, v253
	global_load_dwordx4 v[224:227], v253, s[22:23]
	global_load_dwordx4 v[228:231], v253, s[24:25]
	global_load_dwordx4 v[232:235], v253, s[26:27]
	global_load_dwordx4 v[236:239], v253, s[36:37]
	s_add_u32 s11, s68, 0x100
	v_mov_b32_e32 v84, 0
	s_addc_u32 s33, s69, 0
	s_mov_b32 s49, -2
	v_mov_b32_e32 v85, v84
	v_mov_b32_e32 v86, v84
	v_mov_b32_e32 v87, v84
	v_mov_b32_e32 v76, v84
	s_waitcnt lgkmcnt(0)
	v_mov_b32_e32 v77, v84
	v_mov_b32_e32 v78, v84
	v_mov_b32_e32 v79, v84
	v_mov_b32_e32 v72, v84
	v_mov_b32_e32 v73, v84
	v_mov_b32_e32 v74, v84
	v_mov_b32_e32 v75, v84
	v_mov_b32_e32 v16, v84
	v_mov_b32_e32 v17, v84
	v_mov_b32_e32 v18, v84
	v_mov_b32_e32 v19, v84
	v_mov_b32_e32 v12, v84
	v_mov_b32_e32 v13, v84
	v_mov_b32_e32 v14, v84
	v_mov_b32_e32 v15, v84
	v_mov_b32_e32 v100, v84
	v_mov_b32_e32 v101, v84
	v_mov_b32_e32 v102, v84
	v_mov_b32_e32 v103, v84
	v_mov_b32_e32 v64, v84
	v_mov_b32_e32 v65, v84
	v_mov_b32_e32 v66, v84
	v_mov_b32_e32 v67, v84
	v_mov_b32_e32 v68, v84
	v_mov_b32_e32 v69, v84
	v_mov_b32_e32 v70, v84
	v_mov_b32_e32 v71, v84
	v_mov_b32_e32 v0, v84
	v_mov_b32_e32 v1, v84
	v_mov_b32_e32 v2, v84
	v_mov_b32_e32 v3, v84
	v_mov_b32_e32 v4, v84
	v_mov_b32_e32 v5, v84
	v_mov_b32_e32 v6, v84
	v_mov_b32_e32 v7, v84
	v_mov_b32_e32 v32, v84
	v_mov_b32_e32 v33, v84
	v_mov_b32_e32 v34, v84
	v_mov_b32_e32 v35, v84
	v_mov_b32_e32 v36, v84
	v_mov_b32_e32 v37, v84
	v_mov_b32_e32 v38, v84
	v_mov_b32_e32 v39, v84
	v_mov_b32_e32 v8, v84
	v_mov_b32_e32 v9, v84
	v_mov_b32_e32 v10, v84
	v_mov_b32_e32 v11, v84
	v_mov_b32_e32 v40, v84
	v_mov_b32_e32 v41, v84
	v_mov_b32_e32 v42, v84
	v_mov_b32_e32 v43, v84
	v_mov_b32_e32 v20, v84
	v_mov_b32_e32 v21, v84
	v_mov_b32_e32 v22, v84
	v_mov_b32_e32 v23, v84
	v_mov_b32_e32 v44, v84
	v_mov_b32_e32 v45, v84
	v_mov_b32_e32 v46, v84
	v_mov_b32_e32 v47, v84
	v_mov_b32_e32 v108, v84
	v_mov_b32_e32 v109, v84
	v_mov_b32_e32 v110, v84
	v_mov_b32_e32 v111, v84
	v_mov_b32_e32 v80, v84
	v_mov_b32_e32 v81, v84
	v_mov_b32_e32 v82, v84
	v_mov_b32_e32 v83, v84
	v_mov_b32_e32 v104, v84
	v_mov_b32_e32 v105, v84
	v_mov_b32_e32 v106, v84
	v_mov_b32_e32 v107, v84
	v_mov_b32_e32 v88, v84
	v_mov_b32_e32 v89, v84
	v_mov_b32_e32 v90, v84
	v_mov_b32_e32 v91, v84
	v_mov_b32_e32 v112, v84
	v_mov_b32_e32 v113, v84
	v_mov_b32_e32 v114, v84
	v_mov_b32_e32 v115, v84
	v_mov_b32_e32 v24, v84
	v_mov_b32_e32 v25, v84
	v_mov_b32_e32 v26, v84
	v_mov_b32_e32 v27, v84
	v_mov_b32_e32 v48, v84
	v_mov_b32_e32 v49, v84
	v_mov_b32_e32 v50, v84
	v_mov_b32_e32 v51, v84
	v_mov_b32_e32 v28, v84
	v_mov_b32_e32 v29, v84
	v_mov_b32_e32 v30, v84
	v_mov_b32_e32 v31, v84
	v_mov_b32_e32 v52, v84
	v_mov_b32_e32 v53, v84
	v_mov_b32_e32 v54, v84
	v_mov_b32_e32 v55, v84
	v_mov_b32_e32 v56, v84
	v_mov_b32_e32 v57, v84
	v_mov_b32_e32 v58, v84
	v_mov_b32_e32 v59, v84
	v_mov_b32_e32 v60, v84
	v_mov_b32_e32 v61, v84
	v_mov_b32_e32 v62, v84
	v_mov_b32_e32 v63, v84
	v_mov_b32_e32 v92, v84
	v_mov_b32_e32 v93, v84
	v_mov_b32_e32 v94, v84
	v_mov_b32_e32 v95, v84
	v_mov_b32_e32 v116, v84
	v_mov_b32_e32 v117, v84
	v_mov_b32_e32 v118, v84
	v_mov_b32_e32 v119, v84
	v_mov_b32_e32 v96, v84
	v_mov_b32_e32 v97, v84
	v_mov_b32_e32 v98, v84
	v_mov_b32_e32 v99, v84
	v_mov_b32_e32 v120, v84
	v_mov_b32_e32 v121, v84
	v_mov_b32_e32 v122, v84
	v_mov_b32_e32 v123, v84
	v_mov_b32_e32 v124, v84
	v_mov_b32_e32 v125, v84
	v_mov_b32_e32 v126, v84
	v_mov_b32_e32 v127, v84
.LBB0_800:
	ds_read_b128 v[128:131], v158
	ds_read_b128 v[132:135], v158 offset:1024
	ds_read_b128 v[148:151], v158 offset:2048
	ds_read_b128 v[162:165], v158 offset:3072
	s_add_u32 s68, s12, 0x100
	s_addc_u32 s69, s13, 0
	s_cmp_eq_u32 s49, 12
	s_cselect_b32 s73, s63, s69
	s_cselect_b32 s72, s62, s68
	s_cselect_b32 s71, s65, s33
	s_cselect_b32 s70, s64, s11
	v_lshl_add_u64 v[200:201], s[12:13], 0, v[144:145]
	s_add_i32 m0, s67, 0xc000
	ds_read_b128 v[166:169], v159
	ds_read_b128 v[172:175], v159 offset:1024
	ds_read_b128 v[176:179], v159 offset:2048
	ds_read_b128 v[180:183], v159 offset:3072
	ds_read_b128 v[184:187], v159 offset:4096
	ds_read_b128 v[188:191], v159 offset:5120
	ds_read_b128 v[192:195], v159 offset:6144
	ds_read_b128 v[196:199], v159 offset:7168
	global_load_lds_dwordx4 v[200:201], off
	v_lshl_add_u64 v[200:201], s[12:13], 0, v[146:147]
	s_add_i32 m0, s67, 0xe000
	s_nop 0
	global_load_lds_dwordx4 v[200:201], off
	s_waitcnt lgkmcnt(8)
	s_barrier
	s_waitcnt lgkmcnt(0)
	s_setprio 1
	s_waitcnt lgkmcnt(0)
	v_mfma_f32_16x16x32_bf16 v[84:87], v[128:131], v[166:169], v[84:87]
	v_mfma_f32_16x16x32_bf16 v[76:79], v[148:151], v[166:169], v[76:79]
	v_mfma_f32_16x16x32_bf16 v[124:127], v[128:131], v[176:179], v[124:127]
	v_mfma_f32_16x16x32_bf16 v[72:75], v[148:151], v[176:179], v[72:75]
	v_mfma_f32_16x16x32_bf16 v[120:123], v[128:131], v[184:187], v[120:123]
	v_mfma_f32_16x16x32_bf16 v[96:99], v[148:151], v[184:187], v[96:99]
	v_mfma_f32_16x16x32_bf16 v[116:119], v[128:131], v[192:195], v[116:119]
	v_mfma_f32_16x16x32_bf16 v[92:95], v[148:151], v[192:195], v[92:95]
	v_mfma_f32_16x16x32_bf16 v[84:87], v[132:135], v[172:175], v[84:87]
	v_mfma_f32_16x16x32_bf16 v[76:79], v[162:165], v[172:175], v[76:79]
	v_mfma_f32_16x16x32_bf16 v[124:127], v[132:135], v[180:183], v[124:127]
	v_mfma_f32_16x16x32_bf16 v[72:75], v[162:165], v[180:183], v[72:75]
	v_mfma_f32_16x16x32_bf16 v[120:123], v[132:135], v[188:191], v[120:123]
	v_mfma_f32_16x16x32_bf16 v[96:99], v[162:165], v[188:191], v[96:99]
	v_mfma_f32_16x16x32_bf16 v[116:119], v[132:135], v[196:199], v[116:119]
	v_mfma_f32_16x16x32_bf16 v[92:95], v[162:165], v[196:199], v[92:95]
	s_setprio 0
	s_barrier
; #define PG8_STAGE(bufoff, gbase, voff) do { _Pragma("unroll") for (int _i = 0; _i < 2; ++_i) \
;         __builtin_amdgcn_global_load_lds((const unsigned*)((const char*)(gbase) + (voff)[_i]), (LAS unsigned*)(lds + (bufoff) + ldsw + _i * 8192), 16, 0, 0); } while (0)
; #define PG8_LDA(dst, b, h) do { _Pragma("unroll") for (int m = 0; m < 4; ++m) _Pragma("unroll") for (int k = 0; k < 2; ++k) dst[m][k] = *(const LAS bf16x8*)(lds + PG8_SA(b, h) + aoff + m * 2048 + k * 1024); } while (0)
; #define PG8_LDB(dst, b, h) do { _Pragma("unroll") for (int n = 0; n < 2; ++n) _Pragma("unroll") for (int k = 0; k < 2; ++k) dst[n][k] = *(const LAS bf16x8*)(lds + PG8_SB(b, h) + boff + n * 2048 + k * 1024); } while (0)
; #define PG8_MMA(ai, bj, At, Bt) do { __builtin_amdgcn_s_setprio(1); _Pragma("unroll") for (int m = 0; m < 4; ++m) _Pragma("unroll") for (int n = 0; n < 2; ++n) _Pragma("unroll") for (int k = 0; k < 2; ++k) \
;         acc[ai][bj][m][n] = __builtin_amdgcn_mfma_f32_16x16x32_bf16(Bt[n][k], At[m][k], acc[ai][bj][m][n], 0, 0, 0); __builtin_amdgcn_s_setprio(0); } while (0)
; #define PG8_WAIT_V(n) asm volatile("s_waitcnt vmcnt(" #n ")" ::: "memory")
; #define PG8_WAIT_L(n) asm volatile("s_waitcnt lgkmcnt(" #n ")" ::: "memory")
; #define PG8_BAR __builtin_amdgcn_s_barrier()
; #define PG8_SCHED __builtin_amdgcn_sched_barrier(0)
; template <class Epi, class Sched>
; __device__ __forceinline__ void gemm_phase(LAS unsigned char* lds, const int K, const Sched& S, const Epi& E) {
;     ...
;             PG8_LDB(B1, 0, 1); PG8_STAGE(PG8_SB(0, 0), b2, voffB);
;             PG8_BAR; PG8_WAIT_L(0); PG8_MMA(0, 1, At, B1); PG8_BAR;
;             PG8_LDA(At, 0, 1); PG8_STAGE(PG8_SA(0, 0), a2, voffA);
;             PG8_BAR; PG8_WAIT_L(0); PG8_MMA(1, 0, At, B0); PG8_BAR; PG8_SCHED;
;             PG8_STAGE(PG8_SB(0, 1), b2 + hstep, voffB);
;             PG8_WAIT_V(6); PG8_BAR; PG8_MMA(1, 1, At, B1); PG8_BAR;
;             PG8_LDB(B0, 1, 0); PG8_SCHED; PG8_LDA(At, 1, 0); PG8_STAGE(PG8_SA(0, 1), a2 + hstepA, voffA);
;             PG8_WAIT_L(8); PG8_BAR; PG8_WAIT_L(0); PG8_MMA(0, 0, At, B0); PG8_BAR; PG8_SCHED;
	s_add_i32 s12, s88, s78
	v_lshl_add_u64 v[216:217], s[70:71], 0, v[138:139]
	s_mov_b32 m0, s12
	ds_read_b128 v[200:203], v160
	ds_read_b128 v[204:207], v160 offset:1024
	ds_read_b128 v[208:211], v160 offset:2048
	ds_read_b128 v[212:215], v160 offset:3072
	global_load_lds_dwordx4 v[216:217], off
	v_lshl_add_u64 v[218:219], s[70:71], 0, v[142:143]
	s_add_i32 m0, s12, 0x2000
	s_nop 0
	global_load_lds_dwordx4 v[218:219], off
	s_barrier
	s_waitcnt lgkmcnt(0)
	s_setprio 1
	s_waitcnt lgkmcnt(0)
	v_mfma_f32_16x16x32_bf16 v[60:63], v[200:203], v[166:169], v[60:63]
	v_mfma_f32_16x16x32_bf16 v[16:19], v[208:211], v[166:169], v[16:19]
	v_mfma_f32_16x16x32_bf16 v[56:59], v[200:203], v[176:179], v[56:59]
	v_mfma_f32_16x16x32_bf16 v[12:15], v[208:211], v[176:179], v[12:15]
	v_mfma_f32_16x16x32_bf16 v[52:55], v[200:203], v[184:187], v[52:55]
	v_mfma_f32_16x16x32_bf16 v[28:31], v[208:211], v[184:187], v[28:31]
	v_mfma_f32_16x16x32_bf16 v[48:51], v[200:203], v[192:195], v[48:51]
	v_mfma_f32_16x16x32_bf16 v[24:27], v[208:211], v[192:195], v[24:27]
	v_mfma_f32_16x16x32_bf16 v[60:63], v[204:207], v[172:175], v[60:63]
	v_mfma_f32_16x16x32_bf16 v[16:19], v[212:215], v[172:175], v[16:19]
	v_mfma_f32_16x16x32_bf16 v[56:59], v[204:207], v[180:183], v[56:59]
	v_mfma_f32_16x16x32_bf16 v[12:15], v[212:215], v[180:183], v[12:15]
	v_mfma_f32_16x16x32_bf16 v[52:55], v[204:207], v[188:191], v[52:55]
	v_mfma_f32_16x16x32_bf16 v[28:31], v[212:215], v[188:191], v[28:31]
	v_mfma_f32_16x16x32_bf16 v[48:51], v[204:207], v[196:199], v[48:51]
	v_mfma_f32_16x16x32_bf16 v[24:27], v[212:215], v[196:199], v[24:27]
	s_setprio 0
	s_mov_b32 m0, s67
	v_lshl_add_u64 v[220:221], s[72:73], 0, v[136:137]
	s_barrier
	ds_read_b128 v[166:169], v159 offset:16384
	ds_read_b128 v[172:175], v159 offset:17408
	ds_read_b128 v[176:179], v159 offset:18432
	ds_read_b128 v[180:183], v159 offset:19456
	ds_read_b128 v[184:187], v159 offset:20480
	ds_read_b128 v[188:191], v159 offset:21504
	ds_read_b128 v[192:195], v159 offset:22528
	ds_read_b128 v[196:199], v159 offset:23552
	global_load_lds_dwordx4 v[220:221], off
	v_lshl_add_u64 v[222:223], s[72:73], 0, v[140:141]
	s_mov_b32 m0, s80
	s_nop 0
	global_load_lds_dwordx4 v[222:223], off
	s_barrier
	s_waitcnt lgkmcnt(0)
	s_setprio 1
	s_waitcnt lgkmcnt(0)
	v_mfma_f32_16x16x32_bf16 v[112:115], v[128:131], v[166:169], v[112:115]
	v_mfma_f32_16x16x32_bf16 v[88:91], v[148:151], v[166:169], v[88:91]
	v_mfma_f32_16x16x32_bf16 v[104:107], v[128:131], v[176:179], v[104:107]
	v_mfma_f32_16x16x32_bf16 v[80:83], v[148:151], v[176:179], v[80:83]
	v_mfma_f32_16x16x32_bf16 v[100:103], v[128:131], v[184:187], v[100:103]
	v_mfma_f32_16x16x32_bf16 v[64:67], v[148:151], v[184:187], v[64:67]
	v_mfma_f32_16x16x32_bf16 v[108:111], v[128:131], v[192:195], v[108:111]
	v_mfma_f32_16x16x32_bf16 v[68:71], v[148:151], v[192:195], v[68:71]
	v_mfma_f32_16x16x32_bf16 v[112:115], v[132:135], v[172:175], v[112:115]
	v_mfma_f32_16x16x32_bf16 v[88:91], v[162:165], v[172:175], v[88:91]
	v_mfma_f32_16x16x32_bf16 v[104:107], v[132:135], v[180:183], v[104:107]
	v_mfma_f32_16x16x32_bf16 v[80:83], v[162:165], v[180:183], v[80:83]
	v_mfma_f32_16x16x32_bf16 v[100:103], v[132:135], v[188:191], v[100:103]
	v_mfma_f32_16x16x32_bf16 v[64:67], v[162:165], v[188:191], v[64:67]
	v_mfma_f32_16x16x32_bf16 v[108:111], v[132:135], v[196:199], v[108:111]
	v_mfma_f32_16x16x32_bf16 v[68:71], v[162:165], v[196:199], v[68:71]
	s_setprio 0
	s_barrier
	s_add_u32 s12, s70, 0x40000
	s_addc_u32 s13, s71, 0
	s_add_i32 s52, s89, s78
	v_lshl_add_u64 v[128:129], s[12:13], 0, v[138:139]
	s_mov_b32 m0, s52
	s_nop 0
	global_load_lds_dwordx4 v[128:129], off
	v_lshl_add_u64 v[128:129], s[12:13], 0, v[142:143]
	s_add_i32 m0, s52, 0x2000
	s_nop 0
	global_load_lds_dwordx4 v[128:129], off
	s_waitcnt vmcnt(6)
	s_barrier
	s_setprio 1
	v_mfma_f32_16x16x32_bf16 v[44:47], v[200:203], v[166:169], v[44:47]
	v_mfma_f32_16x16x32_bf16 v[20:23], v[208:211], v[166:169], v[20:23]
	v_mfma_f32_16x16x32_bf16 v[40:43], v[200:203], v[176:179], v[40:43]
	v_mfma_f32_16x16x32_bf16 v[8:11], v[208:211], v[176:179], v[8:11]
	v_mfma_f32_16x16x32_bf16 v[36:39], v[200:203], v[184:187], v[36:39]
	v_mfma_f32_16x16x32_bf16 v[0:3], v[208:211], v[184:187], v[0:3]
	v_mfma_f32_16x16x32_bf16 v[32:35], v[200:203], v[192:195], v[32:35]
	v_mfma_f32_16x16x32_bf16 v[4:7], v[208:211], v[192:195], v[4:7]
	v_mfma_f32_16x16x32_bf16 v[44:47], v[204:207], v[172:175], v[44:47]
	v_mfma_f32_16x16x32_bf16 v[20:23], v[212:215], v[172:175], v[20:23]
	v_mfma_f32_16x16x32_bf16 v[40:43], v[204:207], v[180:183], v[40:43]
	v_mfma_f32_16x16x32_bf16 v[8:11], v[212:215], v[180:183], v[8:11]
	v_mfma_f32_16x16x32_bf16 v[36:39], v[204:207], v[188:191], v[36:39]
	v_mfma_f32_16x16x32_bf16 v[0:3], v[212:215], v[188:191], v[0:3]
	v_mfma_f32_16x16x32_bf16 v[32:35], v[204:207], v[196:199], v[32:35]
	v_mfma_f32_16x16x32_bf16 v[4:7], v[212:215], v[196:199], v[4:7]
	s_setprio 0
	s_add_i32 s52, 0, 0x18000
	v_add_u32_e32 v161, s52, v156
	s_barrier
	ds_read_b128 v[128:131], v161
	ds_read_b128 v[132:135], v161 offset:1024
	ds_read_b128 v[148:151], v161 offset:2048
	ds_read_b128 v[162:165], v161 offset:3072
	s_add_u32 s12, s72, 0x20000
	s_addc_u32 s13, s73, 0
	s_mov_b32 m0, s81
	v_lshl_add_u64 v[200:201], s[12:13], 0, v[136:137]
	ds_read_b128 v[166:169], v159 offset:32768
	ds_read_b128 v[172:175], v159 offset:33792
	ds_read_b128 v[176:179], v159 offset:34816
	ds_read_b128 v[180:183], v159 offset:35840
	ds_read_b128 v[184:187], v159 offset:36864
	ds_read_b128 v[188:191], v159 offset:37888
	ds_read_b128 v[192:195], v159 offset:38912
	ds_read_b128 v[196:199], v159 offset:39936
	global_load_lds_dwordx4 v[200:201], off
	v_lshl_add_u64 v[200:201], s[12:13], 0, v[140:141]
	s_mov_b32 m0, s82
	s_nop 0
	global_load_lds_dwordx4 v[200:201], off
	s_waitcnt lgkmcnt(8)
	s_barrier
; __device__ __forceinline__ unsigned cvt_pk_bf16(float lo, float hi) { unsigned r; asm volatile("v_cvt_pk_bf16_f32 %0, %1, %2" : "=v"(r) : "v"(lo), "v"(hi)); return r; }
; #define PG8_STAGE(bufoff, gbase, voff) do { _Pragma("unroll") for (int _i = 0; _i < 2; ++_i) \
;         __builtin_amdgcn_global_load_lds((const unsigned*)((const char*)(gbase) + (voff)[_i]), (LAS unsigned*)(lds + (bufoff) + ldsw + _i * 8192), 16, 0, 0); } while (0)
; template <class Epi, class Sched>
; __device__ __forceinline__ void gemm_phase(LAS unsigned char* lds, const int K, const Sched& S, const Epi& E) {
;     ...
;             PG8_WAIT_L(8); PG8_BAR; PG8_WAIT_L(0); PG8_MMA(0, 0, At, B0); PG8_BAR; PG8_SCHED;
;             PG8_LDB(B1, 1, 1); PG8_STAGE(PG8_SB(1, 0), b3, voffB);
;             PG8_BAR; PG8_WAIT_L(0); PG8_MMA(0, 1, At, B1); PG8_BAR;
;             PG8_LDA(At, 1, 1); PG8_STAGE(PG8_SA(1, 0), a3, voffA);
;             PG8_BAR; PG8_WAIT_L(0); PG8_MMA(1, 0, At, B0); PG8_BAR; PG8_SCHED;
;             PG8_STAGE(PG8_SB(1, 1), b3 + hstep, voffB);
;             PG8_WAIT_V(6); PG8_BAR; PG8_MMA(1, 1, At, B1); PG8_BAR;
;     __device__ __forceinline__ void operator()(f32x4 (&acc)[2][2][4][2], const Unit& u, int wr, int wc, int fr, int fq) const {
;         const int J0 = u.pn * 128 + wc * 32 + fq * 8, sc = u.pm * 2 + wr;
;         const bool f0 = (fr == 0), f15 = (fr == 15);
;         if (f0 || f15) {
; #pragma unroll
;             for (int bj = 0; bj < 2; ++bj)
; #pragma unroll
;                 for (int q = 0; q < 2; ++q) { const f32x4 a0 = f0 ? acc[0][bj][q][0] : acc[1][bj][2 + q][0], a1 = f0 ? acc[0][bj][q][1] : acc[1][bj][2 + q][1];
;                     u32x4 w; w.x = cvt_pk_bf16(a0[0], a0[1]); w.y = cvt_pk_bf16(a0[2], a0[3]); w.z = cvt_pk_bf16(a1[0], a1[1]); w.w = cvt_pk_bf16(a1[2], a1[3]);
;                     *(u32x4*)(side + (size_t)(sc * 4 + (f0 ? q : 2 + q)) * (2 * DFF) + bj * DFF + J0) = w; }
;         }
; #pragma unroll
;         for (int bj = 0; bj < 2; ++bj)
; #pragma unroll
;             for (int n = 0; n < 2; ++n) {
;                 const int col = bj * DFF + J0 + n * 4;
;                 const float csc = bj ? 0.6931471805599453f : 1.4426950408889634f;
;                 const f32x4 k0 = *(const f32x4*)(cw + col) * csc, k1 = *(const f32x4*)(cw + 2 * DFF + col) * csc, k2 = *(const f32x4*)(cw + 4 * DFF + col) * csc, kb = *(const f32x4*)(cb + col) * csc;
	s_waitcnt lgkmcnt(0)
	s_setprio 1
	s_waitcnt lgkmcnt(0)
	v_mfma_f32_16x16x32_bf16 v[84:87], v[128:131], v[166:169], v[84:87]
	v_mfma_f32_16x16x32_bf16 v[76:79], v[148:151], v[166:169], v[76:79]
	v_mfma_f32_16x16x32_bf16 v[124:127], v[128:131], v[176:179], v[124:127]
	v_mfma_f32_16x16x32_bf16 v[72:75], v[148:151], v[176:179], v[72:75]
	v_mfma_f32_16x16x32_bf16 v[120:123], v[128:131], v[184:187], v[120:123]
	v_mfma_f32_16x16x32_bf16 v[96:99], v[148:151], v[184:187], v[96:99]
	v_mfma_f32_16x16x32_bf16 v[116:119], v[128:131], v[192:195], v[116:119]
	v_mfma_f32_16x16x32_bf16 v[92:95], v[148:151], v[192:195], v[92:95]
	v_mfma_f32_16x16x32_bf16 v[84:87], v[132:135], v[172:175], v[84:87]
	v_mfma_f32_16x16x32_bf16 v[76:79], v[162:165], v[172:175], v[76:79]
	v_mfma_f32_16x16x32_bf16 v[124:127], v[132:135], v[180:183], v[124:127]
	v_mfma_f32_16x16x32_bf16 v[72:75], v[162:165], v[180:183], v[72:75]
	v_mfma_f32_16x16x32_bf16 v[120:123], v[132:135], v[188:191], v[120:123]
	v_mfma_f32_16x16x32_bf16 v[96:99], v[162:165], v[188:191], v[96:99]
	v_mfma_f32_16x16x32_bf16 v[116:119], v[132:135], v[196:199], v[116:119]
	v_mfma_f32_16x16x32_bf16 v[92:95], v[162:165], v[196:199], v[92:95]
	s_setprio 0
	s_barrier
	s_add_i32 s53, 0, 0x1c000
	s_add_i32 s12, s52, s78
	v_add_u32_e32 v161, s53, v156
	v_lshl_add_u64 v[216:217], v[216:217], 0, s[38:39]
	s_mov_b32 m0, s12
	ds_read_b128 v[200:203], v161
	ds_read_b128 v[204:207], v161 offset:1024
	ds_read_b128 v[208:211], v161 offset:2048
	ds_read_b128 v[212:215], v161 offset:3072
	global_load_lds_dwordx4 v[216:217], off
	v_lshl_add_u64 v[216:217], v[218:219], 0, s[38:39]
	s_add_i32 m0, s12, 0x2000
	s_nop 0
	global_load_lds_dwordx4 v[216:217], off
	s_barrier
	s_waitcnt lgkmcnt(0)
	s_setprio 1
	s_waitcnt lgkmcnt(0)
	v_mfma_f32_16x16x32_bf16 v[60:63], v[200:203], v[166:169], v[60:63]
	v_mfma_f32_16x16x32_bf16 v[16:19], v[208:211], v[166:169], v[16:19]
	v_mfma_f32_16x16x32_bf16 v[56:59], v[200:203], v[176:179], v[56:59]
	v_mfma_f32_16x16x32_bf16 v[12:15], v[208:211], v[176:179], v[12:15]
	v_mfma_f32_16x16x32_bf16 v[52:55], v[200:203], v[184:187], v[52:55]
	v_mfma_f32_16x16x32_bf16 v[28:31], v[208:211], v[184:187], v[28:31]
	v_mfma_f32_16x16x32_bf16 v[48:51], v[200:203], v[192:195], v[48:51]
	v_mfma_f32_16x16x32_bf16 v[24:27], v[208:211], v[192:195], v[24:27]
	v_mfma_f32_16x16x32_bf16 v[60:63], v[204:207], v[172:175], v[60:63]
	v_mfma_f32_16x16x32_bf16 v[16:19], v[212:215], v[172:175], v[16:19]
	v_mfma_f32_16x16x32_bf16 v[56:59], v[204:207], v[180:183], v[56:59]
	v_mfma_f32_16x16x32_bf16 v[12:15], v[212:215], v[180:183], v[12:15]
	v_mfma_f32_16x16x32_bf16 v[52:55], v[204:207], v[188:191], v[52:55]
	v_mfma_f32_16x16x32_bf16 v[28:31], v[212:215], v[188:191], v[28:31]
	v_mfma_f32_16x16x32_bf16 v[48:51], v[204:207], v[196:199], v[48:51]
	v_mfma_f32_16x16x32_bf16 v[24:27], v[212:215], v[196:199], v[24:27]
	s_setprio 0
	s_mov_b32 m0, s84
	v_lshl_add_u64 v[216:217], v[220:221], 0, s[38:39]
	s_barrier
	ds_read_b128 v[166:169], v159 offset:49152
	ds_read_b128 v[172:175], v159 offset:50176
	ds_read_b128 v[176:179], v159 offset:51200
	ds_read_b128 v[180:183], v159 offset:52224
	ds_read_b128 v[184:187], v159 offset:53248
	ds_read_b128 v[188:191], v159 offset:54272
	ds_read_b128 v[192:195], v159 offset:55296
	ds_read_b128 v[196:199], v159 offset:56320
	global_load_lds_dwordx4 v[216:217], off
	v_lshl_add_u64 v[216:217], v[222:223], 0, s[38:39]
	s_mov_b32 m0, s85
	s_nop 0
	global_load_lds_dwordx4 v[216:217], off
	s_barrier
	s_waitcnt lgkmcnt(0)
	s_setprio 1
	s_waitcnt lgkmcnt(0)
	v_mfma_f32_16x16x32_bf16 v[112:115], v[128:131], v[166:169], v[112:115]
	v_mfma_f32_16x16x32_bf16 v[88:91], v[148:151], v[166:169], v[88:91]
	v_mfma_f32_16x16x32_bf16 v[104:107], v[128:131], v[176:179], v[104:107]
	v_mfma_f32_16x16x32_bf16 v[80:83], v[148:151], v[176:179], v[80:83]
	v_mfma_f32_16x16x32_bf16 v[100:103], v[128:131], v[184:187], v[100:103]
	v_mfma_f32_16x16x32_bf16 v[64:67], v[148:151], v[184:187], v[64:67]
	v_mfma_f32_16x16x32_bf16 v[108:111], v[128:131], v[192:195], v[108:111]
	v_mfma_f32_16x16x32_bf16 v[68:71], v[148:151], v[192:195], v[68:71]
	v_mfma_f32_16x16x32_bf16 v[112:115], v[132:135], v[172:175], v[112:115]
	v_mfma_f32_16x16x32_bf16 v[88:91], v[162:165], v[172:175], v[88:91]
	v_mfma_f32_16x16x32_bf16 v[104:107], v[132:135], v[180:183], v[104:107]
	v_mfma_f32_16x16x32_bf16 v[80:83], v[162:165], v[180:183], v[80:83]
	v_mfma_f32_16x16x32_bf16 v[100:103], v[132:135], v[188:191], v[100:103]
	v_mfma_f32_16x16x32_bf16 v[64:67], v[162:165], v[188:191], v[64:67]
	v_mfma_f32_16x16x32_bf16 v[108:111], v[132:135], v[196:199], v[108:111]
	v_mfma_f32_16x16x32_bf16 v[68:71], v[162:165], v[196:199], v[68:71]
	s_setprio 0
	s_barrier
	s_add_u32 s12, s70, 0x40080
	s_addc_u32 s13, s71, 0
	s_add_i32 s52, s53, s78
	v_lshl_add_u64 v[128:129], s[12:13], 0, v[138:139]
	s_mov_b32 m0, s52
	s_nop 0
	global_load_lds_dwordx4 v[128:129], off
	v_lshl_add_u64 v[128:129], s[12:13], 0, v[142:143]
	s_add_i32 m0, s52, 0x2000
	s_nop 0
	global_load_lds_dwordx4 v[128:129], off
	s_waitcnt vmcnt(6)
	s_barrier
	s_setprio 1
	v_mfma_f32_16x16x32_bf16 v[44:47], v[200:203], v[166:169], v[44:47]
	v_mfma_f32_16x16x32_bf16 v[20:23], v[208:211], v[166:169], v[20:23]
	v_mfma_f32_16x16x32_bf16 v[40:43], v[200:203], v[176:179], v[40:43]
	v_mfma_f32_16x16x32_bf16 v[8:11], v[208:211], v[176:179], v[8:11]
	v_mfma_f32_16x16x32_bf16 v[36:39], v[200:203], v[184:187], v[36:39]
	v_mfma_f32_16x16x32_bf16 v[0:3], v[208:211], v[184:187], v[0:3]
	v_mfma_f32_16x16x32_bf16 v[32:35], v[200:203], v[192:195], v[32:35]
	v_mfma_f32_16x16x32_bf16 v[4:7], v[208:211], v[192:195], v[4:7]
	v_mfma_f32_16x16x32_bf16 v[44:47], v[204:207], v[172:175], v[44:47]
	v_mfma_f32_16x16x32_bf16 v[20:23], v[212:215], v[172:175], v[20:23]
	v_mfma_f32_16x16x32_bf16 v[40:43], v[204:207], v[180:183], v[40:43]
	v_mfma_f32_16x16x32_bf16 v[8:11], v[212:215], v[180:183], v[8:11]
	v_mfma_f32_16x16x32_bf16 v[36:39], v[204:207], v[188:191], v[36:39]
	v_mfma_f32_16x16x32_bf16 v[0:3], v[212:215], v[188:191], v[0:3]
	v_mfma_f32_16x16x32_bf16 v[32:35], v[204:207], v[196:199], v[32:35]
	v_mfma_f32_16x16x32_bf16 v[4:7], v[212:215], v[196:199], v[4:7]
	s_setprio 0
	s_add_i32 s49, s49, 2
	s_add_u32 s11, s11, 0x100
	s_addc_u32 s33, s33, 0
	s_cmp_gt_u32 s49, 13
	s_mov_b64 s[12:13], s[68:69]
	s_barrier
	s_cbranch_scc0 .LBB0_800
	v_lshl_or_b32 v150, s10, 7, v157
	v_add_u32_e32 v254, 0x2c00, v253
	global_load_dwordx4 v[208:211], v253, s[22:23] offset:16
	global_load_dwordx4 v[212:215], v253, s[24:25] offset:16
	global_load_dwordx4 v[216:219], v253, s[26:27] offset:16
	global_load_dwordx4 v[220:223], v253, s[36:37] offset:16
	v_cmp_gt_i32_e32 vcc, 15, v152
	s_mov_b64 s[70:71], -1
	s_and_saveexec_b64 s[68:69], vcc
	s_cbranch_execz .LBB0_805
	v_cmp_eq_u32_e32 vcc, 0, v152
	v_cmp_ne_u32_e64 s[12:13], 0, v152
	s_and_saveexec_b64 s[70:71], s[12:13]
	v_ashrrev_i32_e32 v151, 31, v150
	v_mov_b64_e32 v[148:149], v[150:151]
	s_or_b64 exec, exec, s[70:71]
	s_orn2_b64 s[70:71], vcc, exec

;     __device__ __forceinline__ void operator()(f32x4 (&acc)[2][2][4][2], const Unit& u, int wr, int wc, int fr, int fq) const {
;     ...
;                 const int col = bj * DFF + J0 + n * 4;
;                 const float csc = bj ? 0.6931471805599453f : 1.4426950408889634f;
;                 const f32x4 k0 = *(const f32x4*)(cw + col) * csc, k1 = *(const f32x4*)(cw + 2 * DFF + col) * csc, k2 = *(const f32x4*)(cw + 4 * DFF + col) * csc, kb = *(const f32x4*)(cb + col) * csc;
;                 const f32x4 a0 = acc[0][bj][0][n], a1 = acc[0][bj][1][n], a2 = acc[0][bj][2][n], a3 = acc[0][bj][3][n];
;                 const f32x4 b0 = acc[1][bj][0][n], b1 = acc[1][bj][1][n], b2 = acc[1][bj][2][n], b3 = acc[1][bj][3][n];
;                 f32x4 pa, pb, na, nb;
; #pragma unroll
;                 for (int j = 0; j < 4; ++j) {
;                     const float t = dpp_f<0x121>(a3[j]);
;                     const float s1 = dpp_f<0x111>(b3[j]);
;                     const float un = dpp_f<0x12F>(b0[j]);
;                     const float s0 = dpp_f<0x101>(a0[j]);
;                     pa[j] = t; pb[j] = f0 ? t : s1; na[j] = f15 ? un : s0; nb[j] = un; }
;                 f32x4 o0 = k2 * a1 + (k1 * a0 + (k0 * pa + kb)), o1 = k2 * a2 + (k1 * a1 + (k0 * a0 + kb)), o2 = k2 * a3 + (k1 * a2 + (k0 * a1 + kb)), o3 = k2 * na + (k1 * a3 + (k0 * a2 + kb));
;                 f32x4 q0 = k2 * b1 + (k1 * b0 + (k0 * pb + kb)), q1 = k2 * b2 + (k1 * b1 + (k0 * b0 + kb)), q2 = k2 * b3 + (k1 * b2 + (k0 * b1 + kb)), q3 = k2 * nb + (k1 * b3 + (k0 * b2 + kb));
.LBB0_807:
	s_or_b64 exec, exec, s[12:13]
	v_lshlrev_b64 v[166:167], 2, v[148:149]
	v_lshl_add_u64 v[128:129], s[22:23], 0, v[166:167]
	v_lshl_add_u64 v[132:133], s[26:27], 0, v[166:167]
	v_lshl_add_u64 v[162:163], s[36:37], 0, v[166:167]
	v_lshl_add_u64 v[166:167], s[24:25], 0, v[166:167]
	v_mov_b32_dpp v172, v116 row_ror:1 row_mask:0xf bank_mask:0xf bound_ctrl:1
	v_mov_b32_dpp v161, v108 row_shr:1 row_mask:0xf bank_mask:0xf bound_ctrl:1
	v_mov_b32_dpp v174, v112 row_ror:15 row_mask:0xf bank_mask:0xf bound_ctrl:1
	v_mov_b32_dpp v181, v84 row_shl:1 row_mask:0xf bank_mask:0xf bound_ctrl:1
	v_mov_b32_dpp v173, v117 row_ror:1 row_mask:0xf bank_mask:0xf bound_ctrl:1
	v_mov_b32_dpp v183, v109 row_shr:1 row_mask:0xf bank_mask:0xf bound_ctrl:1
	v_mov_b32_dpp v175, v113 row_ror:15 row_mask:0xf bank_mask:0xf bound_ctrl:1
	v_mov_b32_dpp v184, v85 row_shl:1 row_mask:0xf bank_mask:0xf bound_ctrl:1
	v_mov_b32_dpp v176, v118 row_ror:1 row_mask:0xf bank_mask:0xf bound_ctrl:1
	v_mov_b32_dpp v185, v110 row_shr:1 row_mask:0xf bank_mask:0xf bound_ctrl:1
	v_mov_b32_dpp v177, v119 row_ror:1 row_mask:0xf bank_mask:0xf bound_ctrl:1
	v_mov_b32_dpp v187, v111 row_shr:1 row_mask:0xf bank_mask:0xf bound_ctrl:1
	v_mov_b32_dpp v179, v115 row_ror:15 row_mask:0xf bank_mask:0xf bound_ctrl:1
	v_mov_b32_dpp v188, v87 row_shl:1 row_mask:0xf bank_mask:0xf bound_ctrl:1
	v_cndmask_b32_e64 v180, v161, v172, s[8:9]
	v_cndmask_b32_e64 v182, v181, v174, s[4:5]
	v_cndmask_b32_e64 v181, v183, v173, s[8:9]
	v_cndmask_b32_e64 v183, v184, v175, s[4:5]
	v_cndmask_b32_e64 v184, v185, v176, s[8:9]
	v_cndmask_b32_e64 v185, v187, v177, s[8:9]
	v_cndmask_b32_e64 v187, v188, v179, s[4:5]
	v_mov_b32_dpp v178, v114 row_ror:15 row_mask:0xf bank_mask:0xf bound_ctrl:1
	v_mov_b32_dpp v186, v86 row_shl:1 row_mask:0xf bank_mask:0xf bound_ctrl:1
	v_cndmask_b32_e64 v186, v186, v178, s[4:5]
	v_mov_b32_dpp v161, v68 row_shr:1 row_mask:0xf bank_mask:0xf bound_ctrl:1
	s_waitcnt vmcnt(8)
	v_pk_mul_f32 v[128:129], v[224:225], s[40:41] op_sel_hi:[1,0]
	v_pk_mul_f32 v[130:131], v[226:227], s[40:41] op_sel_hi:[1,0]
	v_pk_mul_f32 v[166:167], v[228:229], s[40:41] op_sel_hi:[1,0]
	v_pk_mul_f32 v[168:169], v[230:231], s[40:41] op_sel_hi:[1,0]
	v_pk_mul_f32 v[132:133], v[232:233], s[40:41] op_sel_hi:[1,0]
	v_pk_fma_f32 v[172:173], v[128:129], v[172:173], v[166:167]
	v_pk_mul_f32 v[134:135], v[234:235], s[40:41] op_sel_hi:[1,0]
	v_pk_mul_f32 v[162:163], v[236:237], s[40:41] op_sel_hi:[1,0]
	v_pk_fma_f32 v[176:177], v[130:131], v[176:177], v[168:169]
	v_pk_fma_f32 v[188:189], v[84:85], v[128:129], v[166:167]
	v_pk_fma_f32 v[190:191], v[86:87], v[130:131], v[168:169]
	v_pk_fma_f32 v[192:193], v[124:125], v[128:129], v[166:167]
	v_pk_fma_f32 v[194:195], v[126:127], v[130:131], v[168:169]
	v_pk_fma_f32 v[196:197], v[120:121], v[128:129], v[166:167]
	v_pk_fma_f32 v[198:199], v[122:123], v[130:131], v[168:169]
	v_pk_fma_f32 v[180:181], v[128:129], v[180:181], v[166:167]
	v_pk_fma_f32 v[184:185], v[130:131], v[184:185], v[168:169]
	v_pk_fma_f32 v[200:201], v[112:113], v[128:129], v[166:167]
	v_pk_fma_f32 v[202:203], v[114:115], v[130:131], v[168:169]
	v_pk_fma_f32 v[204:205], v[104:105], v[128:129], v[166:167]
	v_pk_fma_f32 v[206:207], v[106:107], v[130:131], v[168:169]
	v_pk_fma_f32 v[166:167], v[100:101], v[128:129], v[166:167]
	v_pk_fma_f32 v[128:129], v[102:103], v[130:131], v[168:169]
	v_pk_fma_f32 v[84:85], v[84:85], v[132:133], v[172:173]
	v_pk_fma_f32 v[86:87], v[86:87], v[134:135], v[176:177]
	v_pk_fma_f32 v[168:169], v[126:127], v[134:135], v[190:191]
	v_pk_fma_f32 v[172:173], v[124:125], v[132:133], v[188:189]
	v_pk_fma_f32 v[176:177], v[122:123], v[134:135], v[194:195]
	v_pk_fma_f32 v[188:189], v[120:121], v[132:133], v[192:193]
	v_pk_fma_f32 v[190:191], v[118:119], v[134:135], v[198:199]
	v_pk_fma_f32 v[192:193], v[116:117], v[132:133], v[196:197]
	v_pk_fma_f32 v[114:115], v[114:115], v[134:135], v[184:185]
	v_pk_fma_f32 v[112:113], v[112:113], v[132:133], v[180:181]
	v_pk_fma_f32 v[180:181], v[106:107], v[134:135], v[202:203]
	v_pk_fma_f32 v[184:185], v[104:105], v[132:133], v[200:201]
	v_pk_fma_f32 v[194:195], v[102:103], v[134:135], v[206:207]
	v_pk_fma_f32 v[196:197], v[100:101], v[132:133], v[204:205]
	v_pk_fma_f32 v[134:135], v[110:111], v[134:135], v[128:129]
	v_pk_fma_f32 v[128:129], v[124:125], v[162:163], v[84:85]
	v_pk_fma_f32 v[84:85], v[108:109], v[132:133], v[166:167]
	v_or_b32_e32 v132, 4, v150
	v_pk_mul_f32 v[164:165], v[238:239], s[40:41] op_sel_hi:[1,0]
	v_ashrrev_i32_e32 v133, 31, v132
	v_lshlrev_b64 v[166:167], 2, v[148:149]
	v_pk_fma_f32 v[130:131], v[126:127], v[164:165], v[86:87]
	v_pk_fma_f32 v[124:125], v[120:121], v[162:163], v[172:173]
	v_pk_fma_f32 v[126:127], v[122:123], v[164:165], v[168:169]
	v_pk_fma_f32 v[120:121], v[116:117], v[162:163], v[188:189]
	v_pk_fma_f32 v[122:123], v[118:119], v[164:165], v[176:177]
	v_pk_fma_f32 v[116:117], v[162:163], v[182:183], v[192:193]
	v_pk_fma_f32 v[118:119], v[164:165], v[186:187], v[190:191]
	v_pk_fma_f32 v[112:113], v[104:105], v[162:163], v[112:113]
	v_pk_fma_f32 v[114:115], v[106:107], v[164:165], v[114:115]
	v_pk_fma_f32 v[104:105], v[100:101], v[162:163], v[184:185]
	v_pk_fma_f32 v[106:107], v[102:103], v[164:165], v[180:181]
	v_pk_fma_f32 v[100:101], v[108:109], v[162:163], v[196:197]
	v_pk_fma_f32 v[102:103], v[110:111], v[164:165], v[194:195]
	v_pk_fma_f32 v[84:85], v[162:163], v[174:175], v[84:85]
	v_pk_fma_f32 v[86:87], v[164:165], v[178:179], v[134:135]
	v_lshl_add_u64 v[108:109], s[22:23], 0, v[166:167]
	v_lshlrev_b64 v[162:163], 2, v[132:133]
	v_lshl_add_u64 v[166:167], s[24:25], 0, v[166:167]
	global_load_dwordx4 v[224:227], v254, s[22:23]
;     __device__ __forceinline__ void operator()(f32x4 (&acc)[2][2][4][2], const Unit& u, int wr, int wc, int fr, int fq) const {
;     ...
;                 const int col = bj * DFF + J0 + n * 4;
;                 const float csc = bj ? 0.6931471805599453f : 1.4426950408889634f;
;                 const f32x4 k0 = *(const f32x4*)(cw + col) * csc, k1 = *(const f32x4*)(cw + 2 * DFF + col) * csc, k2 = *(const f32x4*)(cw + 4 * DFF + col) * csc, kb = *(const f32x4*)(cb + col) * csc;
;                 const f32x4 a0 = acc[0][bj][0][n], a1 = acc[0][bj][1][n], a2 = acc[0][bj][2][n], a3 = acc[0][bj][3][n];
;                 const f32x4 b0 = acc[1][bj][0][n], b1 = acc[1][bj][1][n], b2 = acc[1][bj][2][n], b3 = acc[1][bj][3][n];
;                 f32x4 pa, pb, na, nb;
; #pragma unroll
;                 for (int j = 0; j < 4; ++j) {
;                     const float t = dpp_f<0x121>(a3[j]);
;                     const float s1 = dpp_f<0x111>(b3[j]);
;                     const float un = dpp_f<0x12F>(b0[j]);
;                     const float s0 = dpp_f<0x101>(a0[j]);
;                     pa[j] = t; pb[j] = f0 ? t : s1; na[j] = f15 ? un : s0; nb[j] = un; }
;                 f32x4 o0 = k2 * a1 + (k1 * a0 + (k0 * pa + kb)), o1 = k2 * a2 + (k1 * a1 + (k0 * a0 + kb)), o2 = k2 * a3 + (k1 * a2 + (k0 * a1 + kb)), o3 = k2 * na + (k1 * a3 + (k0 * a2 + kb));
;                 f32x4 q0 = k2 * b1 + (k1 * b0 + (k0 * pb + kb)), q1 = k2 * b2 + (k1 * b1 + (k0 * b0 + kb)), q2 = k2 * b3 + (k1 * b2 + (k0 * b1 + kb)), q3 = k2 * nb + (k1 * b3 + (k0 * b2 + kb));
	v_lshl_add_u64 v[132:133], s[26:27], 0, v[162:163]
	global_load_dwordx4 v[228:231], v254, s[24:25]
	v_lshl_add_u64 v[162:163], s[36:37], 0, v[162:163]
	global_load_dwordx4 v[232:235], v254, s[26:27]
	v_mov_b32_dpp v174, v88 row_ror:15 row_mask:0xf bank_mask:0xf bound_ctrl:1
	global_load_dwordx4 v[236:239], v254, s[36:37]
	v_mov_b32_dpp v181, v76 row_shl:1 row_mask:0xf bank_mask:0xf bound_ctrl:1
	v_mov_b32_dpp v173, v93 row_ror:1 row_mask:0xf bank_mask:0xf bound_ctrl:1
	v_mov_b32_dpp v183, v69 row_shr:1 row_mask:0xf bank_mask:0xf bound_ctrl:1
	v_mov_b32_dpp v175, v89 row_ror:15 row_mask:0xf bank_mask:0xf bound_ctrl:1
	v_mov_b32_dpp v184, v77 row_shl:1 row_mask:0xf bank_mask:0xf bound_ctrl:1
	v_mov_b32_dpp v176, v94 row_ror:1 row_mask:0xf bank_mask:0xf bound_ctrl:1
	v_mov_b32_dpp v185, v70 row_shr:1 row_mask:0xf bank_mask:0xf bound_ctrl:1
	v_mov_b32_dpp v177, v95 row_ror:1 row_mask:0xf bank_mask:0xf bound_ctrl:1
	v_mov_b32_dpp v187, v71 row_shr:1 row_mask:0xf bank_mask:0xf bound_ctrl:1
	v_mov_b32_dpp v179, v91 row_ror:15 row_mask:0xf bank_mask:0xf bound_ctrl:1
	v_mov_b32_dpp v188, v79 row_shl:1 row_mask:0xf bank_mask:0xf bound_ctrl:1
	v_mov_b32_dpp v172, v92 row_ror:1 row_mask:0xf bank_mask:0xf bound_ctrl:1
	v_cndmask_b32_e64 v182, v181, v174, s[4:5]
	v_cndmask_b32_e64 v181, v183, v173, s[8:9]
	v_cndmask_b32_e64 v183, v184, v175, s[4:5]
	v_cndmask_b32_e64 v184, v185, v176, s[8:9]
	v_cndmask_b32_e64 v185, v187, v177, s[8:9]
	v_cndmask_b32_e64 v187, v188, v179, s[4:5]
	v_cndmask_b32_e64 v180, v161, v172, s[8:9]
	v_mov_b32_dpp v186, v78 row_shl:1 row_mask:0xf bank_mask:0xf bound_ctrl:1
	v_mov_b32_dpp v178, v90 row_ror:15 row_mask:0xf bank_mask:0xf bound_ctrl:1
	v_lshlrev_b64 v[150:151], 2, v[150:151]
	v_cndmask_b32_e64 v186, v186, v178, s[4:5]
	v_mov_b32_dpp v161, v32 row_shr:1 row_mask:0xf bank_mask:0xf bound_ctrl:1
	s_waitcnt vmcnt(4)
	v_pk_mul_f32 v[188:189], v[210:211], s[40:41] op_sel_hi:[1,0]
	v_pk_mul_f32 v[190:191], v[208:209], s[40:41] op_sel_hi:[1,0]
	v_pk_mul_f32 v[168:169], v[214:215], s[40:41] op_sel_hi:[1,0]
	v_pk_mul_f32 v[166:167], v[212:213], s[40:41] op_sel_hi:[1,0]
	v_pk_mul_f32 v[192:193], v[218:219], s[40:41] op_sel_hi:[1,0]
	v_pk_mul_f32 v[194:195], v[216:217], s[40:41] op_sel_hi:[1,0]
	v_pk_fma_f32 v[108:109], v[190:191], v[172:173], v[166:167]
	v_pk_fma_f32 v[110:111], v[188:189], v[176:177], v[168:169]
	v_pk_mul_f32 v[164:165], v[222:223], s[40:41] op_sel_hi:[1,0]
	v_pk_mul_f32 v[162:163], v[220:221], s[40:41] op_sel_hi:[1,0]
	v_pk_fma_f32 v[132:133], v[76:77], v[190:191], v[166:167]
	v_pk_fma_f32 v[134:135], v[78:79], v[188:189], v[168:169]
	v_pk_fma_f32 v[180:181], v[190:191], v[180:181], v[166:167]
	v_pk_fma_f32 v[184:185], v[188:189], v[184:185], v[168:169]
	v_pk_fma_f32 v[200:201], v[88:89], v[190:191], v[166:167]
	v_pk_fma_f32 v[202:203], v[90:91], v[188:189], v[168:169]
	v_pk_fma_f32 v[78:79], v[78:79], v[192:193], v[110:111]
	v_pk_fma_f32 v[76:77], v[76:77], v[194:195], v[108:109]
	v_pk_fma_f32 v[172:173], v[72:73], v[190:191], v[166:167]
	v_pk_fma_f32 v[176:177], v[74:75], v[188:189], v[168:169]
	v_pk_fma_f32 v[108:109], v[74:75], v[192:193], v[134:135]
	v_pk_fma_f32 v[204:205], v[72:73], v[194:195], v[132:133]
	v_pk_fma_f32 v[90:91], v[90:91], v[192:193], v[184:185]
	v_pk_fma_f32 v[88:89], v[88:89], v[194:195], v[180:181]
	v_pk_fma_f32 v[180:181], v[82:83], v[192:193], v[202:203]
	v_pk_fma_f32 v[184:185], v[80:81], v[194:195], v[200:201]
	v_pk_fma_f32 v[132:133], v[72:73], v[162:163], v[76:77]
	v_pk_fma_f32 v[134:135], v[74:75], v[164:165], v[78:79]
	v_pk_fma_f32 v[72:73], v[80:81], v[190:191], v[166:167]
	v_pk_fma_f32 v[74:75], v[82:83], v[188:189], v[168:169]
	v_pk_fma_f32 v[196:197], v[96:97], v[190:191], v[166:167]
	v_pk_fma_f32 v[198:199], v[98:99], v[188:189], v[168:169]
	v_pk_fma_f32 v[78:79], v[66:67], v[164:165], v[180:181]
	v_pk_fma_f32 v[76:77], v[64:65], v[162:163], v[184:185]
	v_pk_fma_f32 v[74:75], v[66:67], v[192:193], v[74:75]
	v_pk_fma_f32 v[72:73], v[64:65], v[194:195], v[72:73]
	v_pk_fma_f32 v[64:65], v[64:65], v[190:191], v[166:167]
	v_pk_fma_f32 v[66:67], v[66:67], v[188:189], v[168:169]
	v_pk_fma_f32 v[176:177], v[98:99], v[192:193], v[176:177]
	v_pk_fma_f32 v[172:173], v[96:97], v[194:195], v[172:173]
	v_pk_fma_f32 v[198:199], v[94:95], v[192:193], v[198:199]
	v_pk_fma_f32 v[196:197], v[92:93], v[194:195], v[196:197]
	v_pk_fma_f32 v[66:67], v[70:71], v[192:193], v[66:67]
	v_pk_fma_f32 v[64:65], v[68:69], v[194:195], v[64:65]
	v_lshl_add_u64 v[166:167], v[150:151], 0, s[42:43]
	v_pk_fma_f32 v[110:111], v[98:99], v[164:165], v[108:109]
	v_pk_fma_f32 v[108:109], v[96:97], v[162:163], v[204:205]
	v_pk_fma_f32 v[98:99], v[94:95], v[164:165], v[176:177]
	v_pk_fma_f32 v[96:97], v[92:93], v[162:163], v[172:173]
	v_pk_fma_f32 v[92:93], v[162:163], v[182:183], v[196:197]
	v_pk_fma_f32 v[94:95], v[164:165], v[186:187], v[198:199]
	v_pk_fma_f32 v[90:91], v[82:83], v[164:165], v[90:91]
	v_pk_fma_f32 v[88:89], v[80:81], v[162:163], v[88:89]
	v_pk_fma_f32 v[74:75], v[70:71], v[164:165], v[74:75]
	v_pk_fma_f32 v[72:73], v[68:69], v[162:163], v[72:73]
	v_pk_fma_f32 v[66:67], v[164:165], v[178:179], v[66:67]
	v_pk_fma_f32 v[64:65], v[162:163], v[174:175], v[64:65]
	v_lshl_add_u64 v[68:69], s[22:23], 0, v[166:167]
	v_lshl_add_u64 v[80:81], s[26:27], 0, v[166:167]
	v_lshl_add_u64 v[162:163], s[36:37], 0, v[166:167]
	v_lshl_add_u64 v[166:167], s[24:25], 0, v[166:167]
	global_load_dwordx4 v[208:211], v254, s[22:23] offset:16
	v_mov_b32_dpp v172, v48 row_ror:1 row_mask:0xf bank_mask:0xf bound_ctrl:1
	global_load_dwordx4 v[212:215], v254, s[24:25] offset:16
	v_mov_b32_dpp v174, v44 row_ror:15 row_mask:0xf bank_mask:0xf bound_ctrl:1
;     __device__ __forceinline__ void operator()(f32x4 (&acc)[2][2][4][2], const Unit& u, int wr, int wc, int fr, int fq) const {
;     ...
;                 const int col = bj * DFF + J0 + n * 4;
;                 const float csc = bj ? 0.6931471805599453f : 1.4426950408889634f;
;                 const f32x4 k0 = *(const f32x4*)(cw + col) * csc, k1 = *(const f32x4*)(cw + 2 * DFF + col) * csc, k2 = *(const f32x4*)(cw + 4 * DFF + col) * csc, kb = *(const f32x4*)(cb + col) * csc;
;                 const f32x4 a0 = acc[0][bj][0][n], a1 = acc[0][bj][1][n], a2 = acc[0][bj][2][n], a3 = acc[0][bj][3][n];
;                 const f32x4 b0 = acc[1][bj][0][n], b1 = acc[1][bj][1][n], b2 = acc[1][bj][2][n], b3 = acc[1][bj][3][n];
;                 f32x4 pa, pb, na, nb;
; #pragma unroll
;                 for (int j = 0; j < 4; ++j) {
;                     const float t = dpp_f<0x121>(a3[j]);
;                     const float s1 = dpp_f<0x111>(b3[j]);
;                     const float un = dpp_f<0x12F>(b0[j]);
;                     const float s0 = dpp_f<0x101>(a0[j]);
;                     pa[j] = t; pb[j] = f0 ? t : s1; na[j] = f15 ? un : s0; nb[j] = un; }
;                 f32x4 o0 = k2 * a1 + (k1 * a0 + (k0 * pa + kb)), o1 = k2 * a2 + (k1 * a1 + (k0 * a0 + kb)), o2 = k2 * a3 + (k1 * a2 + (k0 * a1 + kb)), o3 = k2 * na + (k1 * a3 + (k0 * a2 + kb));
;                 f32x4 q0 = k2 * b1 + (k1 * b0 + (k0 * pb + kb)), q1 = k2 * b2 + (k1 * b1 + (k0 * b0 + kb)), q2 = k2 * b3 + (k1 * b2 + (k0 * b1 + kb)), q3 = k2 * nb + (k1 * b3 + (k0 * b2 + kb));
	global_load_dwordx4 v[216:219], v254, s[26:27] offset:16
	v_mov_b32_dpp v181, v60 row_shl:1 row_mask:0xf bank_mask:0xf bound_ctrl:1
	global_load_dwordx4 v[220:223], v254, s[36:37] offset:16
	v_mov_b32_dpp v173, v49 row_ror:1 row_mask:0xf bank_mask:0xf bound_ctrl:1
	v_mov_b32_dpp v183, v33 row_shr:1 row_mask:0xf bank_mask:0xf bound_ctrl:1
	v_mov_b32_dpp v175, v45 row_ror:15 row_mask:0xf bank_mask:0xf bound_ctrl:1
	v_mov_b32_dpp v184, v61 row_shl:1 row_mask:0xf bank_mask:0xf bound_ctrl:1
	v_mov_b32_dpp v176, v50 row_ror:1 row_mask:0xf bank_mask:0xf bound_ctrl:1
	v_mov_b32_dpp v185, v34 row_shr:1 row_mask:0xf bank_mask:0xf bound_ctrl:1
	v_mov_b32_dpp v177, v51 row_ror:1 row_mask:0xf bank_mask:0xf bound_ctrl:1
	v_mov_b32_dpp v187, v35 row_shr:1 row_mask:0xf bank_mask:0xf bound_ctrl:1
	v_mov_b32_dpp v179, v47 row_ror:15 row_mask:0xf bank_mask:0xf bound_ctrl:1
	v_mov_b32_dpp v188, v63 row_shl:1 row_mask:0xf bank_mask:0xf bound_ctrl:1
	v_cndmask_b32_e64 v180, v161, v172, s[8:9]
	v_cndmask_b32_e64 v182, v181, v174, s[4:5]
	v_cndmask_b32_e64 v181, v183, v173, s[8:9]
	v_cndmask_b32_e64 v183, v184, v175, s[4:5]
	v_cndmask_b32_e64 v184, v185, v176, s[8:9]
	v_cndmask_b32_e64 v185, v187, v177, s[8:9]
	v_cndmask_b32_e64 v187, v188, v179, s[4:5]
	v_mov_b32_dpp v178, v46 row_ror:15 row_mask:0xf bank_mask:0xf bound_ctrl:1
	v_mov_b32_dpp v186, v62 row_shl:1 row_mask:0xf bank_mask:0xf bound_ctrl:1
	v_cndmask_b32_e64 v186, v186, v178, s[4:5]
	v_lshl_add_u64 v[150:151], v[150:151], 0, s[46:47]
	v_mov_b32_dpp v161, v4 row_shr:1 row_mask:0xf bank_mask:0xf bound_ctrl:1
	s_waitcnt vmcnt(4)
	v_pk_mul_f32 v[188:189], v[226:227], s[44:45] op_sel_hi:[1,0]
	v_pk_mul_f32 v[190:191], v[224:225], s[44:45] op_sel_hi:[1,0]
	v_pk_mul_f32 v[168:169], v[230:231], s[44:45] op_sel_hi:[1,0]
	v_pk_mul_f32 v[166:167], v[228:229], s[44:45] op_sel_hi:[1,0]
	v_pk_mul_f32 v[80:81], v[232:233], s[44:45] op_sel_hi:[1,0]
	v_pk_mul_f32 v[82:83], v[234:235], s[44:45] op_sel_hi:[1,0]
	v_pk_fma_f32 v[68:69], v[190:191], v[172:173], v[166:167]
	v_pk_fma_f32 v[70:71], v[188:189], v[176:177], v[168:169]
	v_pk_fma_f32 v[192:193], v[56:57], v[190:191], v[166:167]
	v_pk_fma_f32 v[194:195], v[58:59], v[188:189], v[168:169]
	v_pk_fma_f32 v[180:181], v[190:191], v[180:181], v[166:167]
	v_pk_fma_f32 v[184:185], v[188:189], v[184:185], v[168:169]
	v_pk_mul_f32 v[164:165], v[238:239], s[44:45] op_sel_hi:[1,0]
	v_pk_mul_f32 v[162:163], v[236:237], s[44:45] op_sel_hi:[1,0]
	v_pk_fma_f32 v[172:173], v[60:61], v[190:191], v[166:167]
	v_pk_fma_f32 v[176:177], v[62:63], v[188:189], v[168:169]
	v_pk_fma_f32 v[196:197], v[52:53], v[190:191], v[166:167]
	v_pk_fma_f32 v[198:199], v[54:55], v[188:189], v[168:169]
	v_pk_fma_f32 v[62:63], v[62:63], v[82:83], v[70:71]
	v_pk_fma_f32 v[60:61], v[60:61], v[80:81], v[68:69]
	v_pk_fma_f32 v[194:195], v[54:55], v[82:83], v[194:195]
	v_pk_fma_f32 v[192:193], v[52:53], v[80:81], v[192:193]
	v_pk_fma_f32 v[184:185], v[46:47], v[82:83], v[184:185]
	v_pk_fma_f32 v[180:181], v[44:45], v[80:81], v[180:181]
	v_pk_fma_f32 v[44:45], v[44:45], v[190:191], v[166:167]
	v_pk_fma_f32 v[46:47], v[46:47], v[188:189], v[168:169]
	v_pk_fma_f32 v[176:177], v[58:59], v[82:83], v[176:177]
	v_pk_fma_f32 v[172:173], v[56:57], v[80:81], v[172:173]
	v_pk_fma_f32 v[198:199], v[50:51], v[82:83], v[198:199]
	v_pk_fma_f32 v[196:197], v[48:49], v[80:81], v[196:197]
	v_pk_fma_f32 v[68:69], v[56:57], v[162:163], v[60:61]
	v_pk_fma_f32 v[70:71], v[58:59], v[164:165], v[62:63]
	v_pk_fma_f32 v[56:57], v[48:49], v[162:163], v[192:193]
	v_pk_fma_f32 v[58:59], v[50:51], v[164:165], v[194:195]
	v_pk_fma_f32 v[48:49], v[40:41], v[162:163], v[180:181]
	v_pk_fma_f32 v[50:51], v[42:43], v[164:165], v[184:185]
	v_pk_fma_f32 v[46:47], v[42:43], v[82:83], v[46:47]
	v_pk_fma_f32 v[44:45], v[40:41], v[80:81], v[44:45]
	v_pk_fma_f32 v[40:41], v[40:41], v[190:191], v[166:167]
	v_pk_fma_f32 v[42:43], v[42:43], v[188:189], v[168:169]
	v_pk_fma_f32 v[44:45], v[36:37], v[162:163], v[44:45]
	v_pk_fma_f32 v[46:47], v[38:39], v[164:165], v[46:47]
	v_pk_fma_f32 v[42:43], v[38:39], v[82:83], v[42:43]
	v_pk_fma_f32 v[40:41], v[36:37], v[80:81], v[40:41]
	v_pk_fma_f32 v[36:37], v[36:37], v[190:191], v[166:167]
	v_pk_fma_f32 v[38:39], v[38:39], v[188:189], v[168:169]
	v_pk_fma_f32 v[40:41], v[32:33], v[162:163], v[40:41]
	v_pk_fma_f32 v[42:43], v[34:35], v[164:165], v[42:43]
	v_pk_fma_f32 v[34:35], v[34:35], v[82:83], v[38:39]
	v_pk_fma_f32 v[32:33], v[32:33], v[80:81], v[36:37]
	v_pk_fma_f32 v[60:61], v[52:53], v[162:163], v[172:173]
	v_pk_fma_f32 v[62:63], v[54:55], v[164:165], v[176:177]
	v_pk_fma_f32 v[52:53], v[162:163], v[182:183], v[196:197]
	v_pk_fma_f32 v[54:55], v[164:165], v[186:187], v[198:199]
	v_pk_fma_f32 v[32:33], v[162:163], v[174:175], v[32:33]
	v_pk_fma_f32 v[34:35], v[164:165], v[178:179], v[34:35]
	v_lshl_add_u64 v[36:37], s[22:23], 0, v[150:151]
	v_lshl_add_u64 v[80:81], s[26:27], 0, v[150:151]
	v_lshl_add_u64 v[162:163], s[36:37], 0, v[150:151]
	v_lshl_add_u64 v[150:151], s[24:25], 0, v[150:151]
	v_mov_b32_dpp v172, v20 row_ror:15 row_mask:0xf bank_mask:0xf bound_ctrl:1
	v_mov_b32_dpp v150, v24 row_ror:1 row_mask:0xf bank_mask:0xf bound_ctrl:1
	v_mov_b32_dpp v151, v25 row_ror:1 row_mask:0xf bank_mask:0xf bound_ctrl:1
	v_mov_b32_dpp v179, v16 row_shl:1 row_mask:0xf bank_mask:0xf bound_ctrl:1
	v_mov_b32_dpp v181, v5 row_shr:1 row_mask:0xf bank_mask:0xf bound_ctrl:1
	v_mov_b32_dpp v182, v17 row_shl:1 row_mask:0xf bank_mask:0xf bound_ctrl:1
	v_cndmask_b32_e64 v178, v161, v150, s[8:9]
	v_cndmask_b32_e64 v180, v179, v172, s[4:5]
	v_cndmask_b32_e64 v179, v181, v151, s[8:9]
	v_mov_b32_dpp v173, v21 row_ror:15 row_mask:0xf bank_mask:0xf bound_ctrl:1
	v_mov_b32_dpp v174, v26 row_ror:1 row_mask:0xf bank_mask:0xf bound_ctrl:1
	v_mov_b32_dpp v183, v6 row_shr:1 row_mask:0xf bank_mask:0xf bound_ctrl:1
	v_mov_b32_dpp v175, v27 row_ror:1 row_mask:0xf bank_mask:0xf bound_ctrl:1
	v_mov_b32_dpp v185, v7 row_shr:1 row_mask:0xf bank_mask:0xf bound_ctrl:1
	v_mov_b32_dpp v177, v23 row_ror:15 row_mask:0xf bank_mask:0xf bound_ctrl:1
	v_mov_b32_dpp v186, v19 row_shl:1 row_mask:0xf bank_mask:0xf bound_ctrl:1
	v_cndmask_b32_e64 v181, v182, v173, s[4:5]
	v_cndmask_b32_e64 v182, v183, v174, s[8:9]
	v_cndmask_b32_e64 v183, v185, v175, s[8:9]
	v_cndmask_b32_e64 v185, v186, v177, s[4:5]
	v_mov_b32_dpp v184, v18 row_shl:1 row_mask:0xf bank_mask:0xf bound_ctrl:1
	v_mov_b32_dpp v176, v22 row_ror:15 row_mask:0xf bank_mask:0xf bound_ctrl:1
	v_cndmask_b32_e64 v184, v184, v176, s[4:5]
	s_waitcnt vmcnt(0)
;     __device__ __forceinline__ void operator()(f32x4 (&acc)[2][2][4][2], const Unit& u, int wr, int wc, int fr, int fq) const {
;     ...
;                 const f32x4 k0 = *(const f32x4*)(cw + col) * csc, k1 = *(const f32x4*)(cw + 2 * DFF + col) * csc, k2 = *(const f32x4*)(cw + 4 * DFF + col) * csc, kb = *(const f32x4*)(cb + col) * csc;
;                 const f32x4 a0 = acc[0][bj][0][n], a1 = acc[0][bj][1][n], a2 = acc[0][bj][2][n], a3 = acc[0][bj][3][n];
;                 const f32x4 b0 = acc[1][bj][0][n], b1 = acc[1][bj][1][n], b2 = acc[1][bj][2][n], b3 = acc[1][bj][3][n];
;                 f32x4 pa, pb, na, nb;
; #pragma unroll
;                 for (int j = 0; j < 4; ++j) {
;                     const float t = dpp_f<0x121>(a3[j]);
;                     const float s1 = dpp_f<0x111>(b3[j]);
;                     const float un = dpp_f<0x12F>(b0[j]);
;                     const float s0 = dpp_f<0x101>(a0[j]);
;                     pa[j] = t; pb[j] = f0 ? t : s1; na[j] = f15 ? un : s0; nb[j] = un; }
;                 f32x4 o0 = k2 * a1 + (k1 * a0 + (k0 * pa + kb)), o1 = k2 * a2 + (k1 * a1 + (k0 * a0 + kb)), o2 = k2 * a3 + (k1 * a2 + (k0 * a1 + kb)), o3 = k2 * na + (k1 * a3 + (k0 * a2 + kb));
;                 f32x4 q0 = k2 * b1 + (k1 * b0 + (k0 * pb + kb)), q1 = k2 * b2 + (k1 * b1 + (k0 * b0 + kb)), q2 = k2 * b3 + (k1 * b2 + (k0 * b1 + kb)), q3 = k2 * nb + (k1 * b3 + (k0 * b2 + kb));
;                 asm volatile("" : "+v"(o0), "+v"(o1), "+v"(o2), "+v"(o3), "+v"(q0), "+v"(q1), "+v"(q2), "+v"(q3));
;                 acc[0][bj][0][n] = o0; acc[0][bj][1][n] = o1; acc[0][bj][2][n] = o2; acc[0][bj][3][n] = o3;
;                 acc[1][bj][0][n] = q0; acc[1][bj][1][n] = q1; acc[1][bj][2][n] = q2; acc[1][bj][3][n] = q3;
;             }
; #pragma unroll
;         for (int ai = 0; ai < 2; ++ai)
; #pragma unroll
;             for (int m = 0; m < 4; ++m) {
;                 const f32x4 g0 = acc[ai][0][m][0], g1 = acc[ai][0][m][1], v0 = acc[ai][1][m][0], v1 = acc[ai][1][m][1];
;     ...
;                 u32x4 w; w.x = cvt_pk_bf16(SG2(g0[0], v0[0]), SG2(g0[1], v0[1])); w.y = cvt_pk_bf16(SG2(g0[2], v0[2]), SG2(g0[3], v0[3]));
;                 w.z = cvt_pk_bf16(SG2(g1[0], v1[0]), SG2(g1[1], v1[1])); w.w = cvt_pk_bf16(SG2(g1[2], v1[2]), SG2(g1[3], v1[3]));
;     ...
;                 const bool valid = !((ai == 0 && m == 0 && f0) || (ai == 1 && m == 3 && f15));
	v_pk_mul_f32 v[188:189], v[208:209], s[44:45] op_sel_hi:[1,0]
	v_pk_mul_f32 v[186:187], v[210:211], s[44:45] op_sel_hi:[1,0]
	v_pk_mul_f32 v[166:167], v[212:213], s[44:45] op_sel_hi:[1,0]
	v_pk_mul_f32 v[168:169], v[214:215], s[44:45] op_sel_hi:[1,0]
	v_pk_mul_f32 v[190:191], v[216:217], s[44:45] op_sel_hi:[1,0]
	v_pk_fma_f32 v[36:37], v[188:189], v[150:151], v[166:167]
	v_pk_mul_f32 v[162:163], v[220:221], s[44:45] op_sel_hi:[1,0]
	v_pk_fma_f32 v[80:81], v[16:17], v[188:189], v[166:167]
	v_pk_fma_f32 v[16:17], v[16:17], v[190:191], v[36:37]
	v_pk_fma_f32 v[150:151], v[12:13], v[188:189], v[166:167]
	v_pk_fma_f32 v[36:37], v[12:13], v[190:191], v[80:81]
	v_pk_fma_f32 v[80:81], v[12:13], v[162:163], v[16:17]
	v_pk_fma_f32 v[12:13], v[188:189], v[178:179], v[166:167]
	v_pk_mul_f32 v[192:193], v[218:219], s[44:45] op_sel_hi:[1,0]
	v_pk_fma_f32 v[12:13], v[20:21], v[190:191], v[12:13]
	v_pk_fma_f32 v[38:39], v[186:187], v[174:175], v[168:169]
	v_pk_fma_f32 v[16:17], v[8:9], v[162:163], v[12:13]
	v_pk_fma_f32 v[12:13], v[20:21], v[188:189], v[166:167]
	v_pk_mul_f32 v[164:165], v[222:223], s[44:45] op_sel_hi:[1,0]
	v_pk_fma_f32 v[12:13], v[8:9], v[190:191], v[12:13]
	v_pk_fma_f32 v[8:9], v[8:9], v[188:189], v[166:167]
	v_pk_fma_f32 v[12:13], v[0:1], v[162:163], v[12:13]
	v_pk_fma_f32 v[8:9], v[0:1], v[190:191], v[8:9]
	v_pk_fma_f32 v[0:1], v[0:1], v[188:189], v[166:167]
	v_pk_fma_f32 v[8:9], v[4:5], v[162:163], v[8:9]
	v_pk_fma_f32 v[0:1], v[4:5], v[190:191], v[0:1]
	v_exp_f32_e64 v4, -v128
	v_exp_f32_e64 v5, -v129
	v_pk_fma_f32 v[82:83], v[18:19], v[186:187], v[168:169]
	v_pk_fma_f32 v[18:19], v[18:19], v[192:193], v[38:39]
	v_pk_fma_f32 v[174:175], v[14:15], v[186:187], v[168:169]
	v_pk_fma_f32 v[38:39], v[14:15], v[192:193], v[82:83]
	v_pk_fma_f32 v[82:83], v[14:15], v[164:165], v[18:19]
	v_pk_fma_f32 v[14:15], v[186:187], v[182:183], v[168:169]
	v_add_f32_e32 v4, 1.0, v4
	v_pk_fma_f32 v[14:15], v[22:23], v[192:193], v[14:15]
	v_rcp_f32_e32 v4, v4
	v_pk_fma_f32 v[18:19], v[10:11], v[164:165], v[14:15]
	v_pk_fma_f32 v[14:15], v[22:23], v[186:187], v[168:169]
	v_add_f32_e32 v5, 1.0, v5
	v_pk_fma_f32 v[14:15], v[10:11], v[192:193], v[14:15]
	v_pk_fma_f32 v[10:11], v[10:11], v[186:187], v[168:169]
	v_rcp_f32_e32 v5, v5
	v_pk_fma_f32 v[14:15], v[2:3], v[164:165], v[14:15]
	v_pk_fma_f32 v[10:11], v[2:3], v[192:193], v[10:11]
	v_pk_fma_f32 v[2:3], v[2:3], v[186:187], v[168:169]
	v_pk_fma_f32 v[194:195], v[28:29], v[188:189], v[166:167]
	v_pk_fma_f32 v[196:197], v[30:31], v[186:187], v[168:169]
	v_pk_fma_f32 v[10:11], v[6:7], v[164:165], v[10:11]
	v_pk_fma_f32 v[2:3], v[6:7], v[192:193], v[2:3]
	v_mul_f32_e32 v6, v128, v68
	v_pk_fma_f32 v[174:175], v[30:31], v[192:193], v[174:175]
	v_pk_fma_f32 v[150:151], v[28:29], v[190:191], v[150:151]
	v_pk_fma_f32 v[196:197], v[26:27], v[192:193], v[196:197]
	v_pk_fma_f32 v[194:195], v[24:25], v[190:191], v[194:195]
	v_mul_f32_e32 v4, v4, v6
	v_mul_f32_e32 v6, v129, v69
	v_pk_fma_f32 v[36:37], v[28:29], v[162:163], v[36:37]
	v_pk_fma_f32 v[38:39], v[30:31], v[164:165], v[38:39]
	v_pk_fma_f32 v[28:29], v[24:25], v[162:163], v[150:151]
	v_pk_fma_f32 v[30:31], v[26:27], v[164:165], v[174:175]
	v_pk_fma_f32 v[24:25], v[162:163], v[180:181], v[194:195]
	v_pk_fma_f32 v[26:27], v[164:165], v[184:185], v[196:197]
	v_pk_fma_f32 v[0:1], v[162:163], v[172:173], v[0:1]
	v_pk_fma_f32 v[2:3], v[164:165], v[176:177], v[2:3]
	v_exp_f32_e64 v7, -v130
	v_mul_f32_e32 v5, v5, v6
	v_cvt_pk_bf16_f32 v4, v4, v5
	v_exp_f32_e64 v5, -v131
	v_add_f32_e32 v6, 1.0, v7
	v_rcp_f32_e32 v6, v6
	v_mul_f32_e32 v7, v130, v70
	v_add_f32_e32 v5, 1.0, v5
	v_rcp_f32_e32 v5, v5
	v_mul_f32_e32 v6, v6, v7
	v_mul_f32_e32 v7, v131, v71
	v_exp_f32_e64 v21, -v132
	v_mul_f32_e32 v5, v5, v7
	v_cvt_pk_bf16_f32 v5, v6, v5
	v_exp_f32_e64 v6, -v133
	v_add_f32_e32 v7, 1.0, v21
	v_rcp_f32_e32 v7, v7
	v_mul_f32_e32 v21, v132, v80
	v_add_f32_e32 v6, 1.0, v6
	v_rcp_f32_e32 v6, v6
	v_mul_f32_e32 v7, v7, v21
	v_mul_f32_e32 v21, v133, v81
	v_exp_f32_e64 v22, -v134
	v_mul_f32_e32 v6, v6, v21
	v_exp_f32_e64 v21, -v135
	v_cvt_pk_bf16_f32 v6, v7, v6
	v_add_f32_e32 v7, 1.0, v22
	v_rcp_f32_e32 v7, v7
	v_add_f32_e32 v21, 1.0, v21
	v_rcp_f32_e32 v21, v21
	v_mul_f32_e32 v22, v134, v82
	v_lshl_or_b32 v20, s10, 7, v155
	v_mul_f32_e32 v7, v7, v22
	v_mul_f32_e32 v22, v135, v83
	v_mul_f32_e32 v21, v21, v22
	v_cvt_pk_bf16_f32 v7, v7, v21
	s_and_saveexec_b64 s[12:13], s[0:1]
	s_cbranch_execz .LBB0_809
	v_mov_b64_e32 v[22:23], s[18:19]
	v_mad_i64_i32 v[22:23], s[10:11], v20, s92, v[22:23]
	v_lshl_add_u64 v[22:23], v[148:149], 1, v[22:23]
	global_store_dwordx4 v[22:23], v[4:7], off sc1

; __global__ void __launch_bounds__(NTHREADS, 2) fwd_megakernel(Params p) {
	.amdhsa_kernel _Z14fwd_megakernel6Params
		.amdhsa_group_segment_fixed_size 0
		.amdhsa_private_segment_fixed_size 0
		.amdhsa_kernarg_size 416
		.amdhsa_user_sgpr_count 2
		.amdhsa_user_sgpr_dispatch_ptr 0
		.amdhsa_user_sgpr_queue_ptr 0
		.amdhsa_user_sgpr_kernarg_segment_ptr 1
		.amdhsa_user_sgpr_dispatch_id 0
		.amdhsa_user_sgpr_kernarg_preload_length 0
		.amdhsa_user_sgpr_kernarg_preload_offset 0
		.amdhsa_user_sgpr_private_segment_size 0
		.amdhsa_uses_dynamic_stack 0
		.amdhsa_enable_private_segment 0
		.amdhsa_system_sgpr_workgroup_id_x 1
		.amdhsa_system_sgpr_workgroup_id_y 0
		.amdhsa_system_sgpr_workgroup_id_z 0
		.amdhsa_system_sgpr_workgroup_info 0
		.amdhsa_system_vgpr_workitem_id 2
		.amdhsa_next_free_vgpr 256
		.amdhsa_next_free_sgpr 100
		.amdhsa_accum_offset 256
		.amdhsa_reserve_vcc 1
		.amdhsa_float_round_mode_32 0
		.amdhsa_float_round_mode_16_64 0
		.amdhsa_float_denorm_mode_32 3
		.amdhsa_float_denorm_mode_16_64 3
		.amdhsa_dx10_clamp 1
		.amdhsa_ieee_mode 1
		.amdhsa_fp16_overflow 0
		.amdhsa_tg_split 0
		.amdhsa_exception_fp_ieee_invalid_op 0
		.amdhsa_exception_fp_denorm_src 0
		.amdhsa_exception_fp_ieee_div_zero 0
		.amdhsa_exception_fp_ieee_overflow 0
		.amdhsa_exception_fp_ieee_underflow 0
		.amdhsa_exception_fp_ieee_inexact 0
		.amdhsa_exception_int_div_zero 0
	.end_amdhsa_kernel

amdhsa.kernels:
  - .agpr_count:     0
    .args:
      - .offset:         0
        .size:           160
        .value_kind:     by_value
      - .offset:         160
        .size:           4
        .value_kind:     hidden_block_count_x
      - .offset:         164
        .size:           4
        .value_kind:     hidden_block_count_y
      - .offset:         168
        .size:           4
        .value_kind:     hidden_block_count_z
      - .offset:         172
        .size:           2
        .value_kind:     hidden_group_size_x
      - .offset:         174
        .size:           2
        .value_kind:     hidden_group_size_y
      - .offset:         176
        .size:           2
        .value_kind:     hidden_group_size_z
      - .offset:         178
        .size:           2
        .value_kind:     hidden_remainder_x
      - .offset:         180
        .size:           2
        .value_kind:     hidden_remainder_y
      - .offset:         182
        .size:           2
        .value_kind:     hidden_remainder_z
      - .offset:         200
        .size:           8
        .value_kind:     hidden_global_offset_x
      - .offset:         208
        .size:           8
        .value_kind:     hidden_global_offset_y
      - .offset:         216
        .size:           8
        .value_kind:     hidden_global_offset_z
      - .offset:         224
        .size:           2
        .value_kind:     hidden_grid_dims
      - .offset:         248
        .size:           8
        .value_kind:     hidden_multigrid_sync_arg
      - .offset:         280
        .size:           4
        .value_kind:     hidden_dynamic_lds_size
    .group_segment_fixed_size: 0
    .kernarg_segment_align: 8
    .kernarg_segment_size: 416
    .language:       OpenCL C
    .language_version:
      - 2
      - 0
    .max_flat_workgroup_size: 512
    .name:           _Z14fwd_megakernel6Params
    .private_segment_fixed_size: 0
    .sgpr_count:     106
    .sgpr_spill_count: 17
    .symbol:         _Z14fwd_megakernel6Params.kd
    .uniform_work_group_size: 1
    .uses_dynamic_stack: false
    .vgpr_count:     256
    .vgpr_spill_count: 0
    .wavefront_size: 64
